# grid barrier: the acquire (buffer_inv sc1) is issued at arrival, before the wait loop, so it completes while waiting instead of after the release
# speedup vs baseline: 1.0307x; 1.0091x over previous
.LBB0_209:
	s_or_b64 exec, exec, s[8:9]
	v_cvt_f32_u32_e32 v4, v2
	s_waitcnt vmcnt(0)
	v_readfirstlane_b32 s6, v3
	v_sub_u32_e32 v3, 0, v2
	v_rcp_iflag_f32_e32 v4, v4
	v_add_u32_e32 v5, s6, v1
	v_mul_f32_e32 v4, 0x4f7ffffe, v4
	v_cvt_u32_f32_e32 v4, v4
	v_mul_lo_u32 v1, v3, v4
	v_mul_hi_u32 v1, v4, v1
	v_add_u32_e32 v1, v4, v1
	v_mul_hi_u32 v1, v5, v1
	v_mul_lo_u32 v3, v1, v2
	v_sub_u32_e32 v3, v5, v3
	v_add_u32_e32 v4, 1, v1
	v_cmp_ge_u32_e32 vcc, v3, v2
	s_nop 1
	v_cndmask_b32_e32 v1, v1, v4, vcc
	v_sub_u32_e32 v4, v3, v2
	v_cndmask_b32_e32 v3, v3, v4, vcc
	v_add_u32_e32 v4, 1, v1
	v_cmp_ge_u32_e32 vcc, v3, v2
	v_add_u32_e32 v3, 1, v5
	s_nop 0
	v_cndmask_b32_e32 v1, v1, v4, vcc
	v_mul_lo_u32 v4, v2, v1
	v_add_u32_e32 v2, v4, v2
	v_cmp_ne_u32_e32 vcc, v3, v2
	s_and_saveexec_b64 s[6:7], vcc
	s_xor_b64 s[6:7], exec, s[6:7]
	s_cbranch_execz .LBB0_223
	s_waitcnt lgkmcnt(0)
	v_mov_b32_e32 v0, 0
	s_add_u32 s12, s22, 0x194d0500
	s_addc_u32 s13, s23, 0
	buffer_inv sc1
	global_load_dword v0, v0, s[12:13] sc1
	s_waitcnt vmcnt(0)
	v_cmp_eq_u32_e32 vcc, v0, v1
	s_and_saveexec_b64 s[8:9], vcc
	s_cbranch_execz .LBB0_222
	s_add_u32 s10, s22, 0x194cd200
	s_addc_u32 s11, s23, 0
	s_mov_b32 s28, 1
	s_mov_b64 s[14:15], 0
	v_mov_b32_e32 v0, 0
	s_branch .LBB0_213

.LBB0_222:
	s_or_b64 exec, exec, s[8:9]
	s_waitcnt vmcnt(0)
	s_nop 0
	s_waitcnt vmcnt(0)
.LBB0_223:
	s_andn2_saveexec_b64 s[6:7], s[6:7]
	s_cbranch_execz .LBB0_243
	s_mov_b64 s[6:7], exec
	buffer_wbl2 sc1
	buffer_inv sc1
	s_waitcnt lgkmcnt(0)
	s_waitcnt vmcnt(0)
	v_mbcnt_lo_u32_b32 v1, s6, 0
	v_mbcnt_hi_u32_b32 v1, s7, v1
	v_cmp_eq_u32_e32 vcc, 0, v1
	s_and_saveexec_b64 s[8:9], vcc
	s_cbranch_execz .LBB0_226
	s_bcnt1_i32_b64 s6, s[6:7]
	v_mov_b32_e32 v2, 0x194d0000
	v_mov_b32_e32 v3, s6
	global_atomic_add v2, v2, v3, s[22:23] offset:1024 sc0

.LBB0_240:
	s_or_b64 exec, exec, s[6:7]
	s_mov_b64 s[6:7], exec
	v_mbcnt_lo_u32_b32 v0, s6, 0
	v_mbcnt_hi_u32_b32 v0, s7, v0
	v_cmp_eq_u32_e32 vcc, 0, v0
	s_waitcnt vmcnt(0)
	s_nop 0
	s_and_saveexec_b64 s[8:9], vcc
	s_cbranch_execz .LBB0_242
	s_bcnt1_i32_b64 s6, s[6:7]
	v_mov_b32_e32 v0, 0x2000
	v_mov_b32_e32 v1, s6
	s_nop 0

.LBB0_682:
	s_or_b64 exec, exec, s[10:11]
	v_cvt_f32_u32_e32 v4, v2
	s_waitcnt vmcnt(0)
	v_readfirstlane_b32 s8, v3
	v_sub_u32_e32 v3, 0, v2
	v_rcp_iflag_f32_e32 v4, v4
	v_add_u32_e32 v5, s8, v1
	v_mul_f32_e32 v4, 0x4f7ffffe, v4
	v_cvt_u32_f32_e32 v4, v4
	v_mul_lo_u32 v1, v3, v4
	v_mul_hi_u32 v1, v4, v1
	v_add_u32_e32 v1, v4, v1
	v_mul_hi_u32 v1, v5, v1
	v_mul_lo_u32 v3, v1, v2
	v_sub_u32_e32 v3, v5, v3
	v_add_u32_e32 v4, 1, v1
	v_cmp_ge_u32_e32 vcc, v3, v2
	s_nop 1
	v_cndmask_b32_e32 v1, v1, v4, vcc
	v_sub_u32_e32 v4, v3, v2
	v_cndmask_b32_e32 v3, v3, v4, vcc
	v_add_u32_e32 v4, 1, v1
	v_cmp_ge_u32_e32 vcc, v3, v2
	v_add_u32_e32 v3, 1, v5
	s_nop 0
	v_cndmask_b32_e32 v1, v1, v4, vcc
	v_mul_lo_u32 v4, v2, v1
	v_add_u32_e32 v2, v4, v2
	v_cmp_ne_u32_e32 vcc, v3, v2
	s_and_saveexec_b64 s[8:9], vcc
	s_xor_b64 s[8:9], exec, s[8:9]
	s_cbranch_execz .LBB0_696
	s_waitcnt lgkmcnt(0)
	v_mov_b32_e32 v0, 0
	s_add_u32 s14, s22, 0x194d0500
	s_addc_u32 s15, s23, 0
	buffer_inv sc1
	global_load_dword v0, v0, s[14:15] sc1
	s_waitcnt vmcnt(0)
	v_cmp_eq_u32_e32 vcc, v0, v1
	s_and_saveexec_b64 s[10:11], vcc
	s_cbranch_execz .LBB0_695
	s_add_u32 s12, s22, 0x194cd200
	s_addc_u32 s13, s23, 0
	s_mov_b32 s30, 1
	s_mov_b64 s[16:17], 0
	v_mov_b32_e32 v0, 0
	s_branch .LBB0_686

.LBB0_695:
	s_or_b64 exec, exec, s[10:11]
	s_waitcnt vmcnt(0)
	s_nop 0
	s_waitcnt vmcnt(0)
.LBB0_696:
	s_andn2_saveexec_b64 s[8:9], s[8:9]
	s_cbranch_execz .LBB0_716
	s_mov_b64 s[8:9], exec
	buffer_wbl2 sc1
	buffer_inv sc1
	s_waitcnt lgkmcnt(0)
	s_waitcnt vmcnt(0)
	v_mbcnt_lo_u32_b32 v1, s8, 0
	v_mbcnt_hi_u32_b32 v1, s9, v1
	v_cmp_eq_u32_e32 vcc, 0, v1
	s_and_saveexec_b64 s[10:11], vcc
	s_cbranch_execz .LBB0_699
	s_bcnt1_i32_b64 s8, s[8:9]
	v_mov_b32_e32 v2, 0x194d0000
	v_mov_b32_e32 v3, s8
	global_atomic_add v2, v2, v3, s[22:23] offset:1024 sc0

.LBB0_713:
	s_or_b64 exec, exec, s[8:9]
	s_mov_b64 s[8:9], exec
	v_mbcnt_lo_u32_b32 v0, s8, 0
	v_mbcnt_hi_u32_b32 v0, s9, v0
	v_cmp_eq_u32_e32 vcc, 0, v0
	s_waitcnt vmcnt(0)
	s_nop 0
	s_and_saveexec_b64 s[10:11], vcc
	s_cbranch_execz .LBB0_715
	s_bcnt1_i32_b64 s8, s[8:9]
	v_mov_b32_e32 v0, 0x2000
	v_mov_b32_e32 v1, s8
	s_nop 0

.LBB0_1291:
	s_or_b64 exec, exec, s[10:11]
	v_cvt_f32_u32_e32 v4, v2
	s_waitcnt vmcnt(0)
	v_readfirstlane_b32 s8, v3
	v_sub_u32_e32 v3, 0, v2
	v_rcp_iflag_f32_e32 v4, v4
	v_add_u32_e32 v5, s8, v1
	v_mul_f32_e32 v4, 0x4f7ffffe, v4
	v_cvt_u32_f32_e32 v4, v4
	v_mul_lo_u32 v1, v3, v4
	v_mul_hi_u32 v1, v4, v1
	v_add_u32_e32 v1, v4, v1
	v_mul_hi_u32 v1, v5, v1
	v_mul_lo_u32 v3, v1, v2
	v_sub_u32_e32 v3, v5, v3
	v_add_u32_e32 v4, 1, v1
	v_cmp_ge_u32_e32 vcc, v3, v2
	s_nop 1
	v_cndmask_b32_e32 v1, v1, v4, vcc
	v_sub_u32_e32 v4, v3, v2
	v_cndmask_b32_e32 v3, v3, v4, vcc
	v_add_u32_e32 v4, 1, v1
	v_cmp_ge_u32_e32 vcc, v3, v2
	v_add_u32_e32 v3, 1, v5
	s_nop 0
	v_cndmask_b32_e32 v1, v1, v4, vcc
	v_mul_lo_u32 v4, v2, v1
	v_add_u32_e32 v2, v4, v2
	v_cmp_ne_u32_e32 vcc, v3, v2
	s_and_saveexec_b64 s[8:9], vcc
	s_xor_b64 s[8:9], exec, s[8:9]
	s_cbranch_execz .LBB0_1305
	s_waitcnt lgkmcnt(0)
	v_mov_b32_e32 v0, 0
	s_add_u32 s14, s22, 0x194d0500
	s_addc_u32 s15, s23, 0
	buffer_inv sc1
	global_load_dword v0, v0, s[14:15] sc1
	s_waitcnt vmcnt(0)
	v_cmp_eq_u32_e32 vcc, v0, v1
	s_and_saveexec_b64 s[10:11], vcc
	s_cbranch_execz .LBB0_1304
	s_add_u32 s12, s22, 0x194cd200
	s_mov_b32 s34, s30
	s_addc_u32 s13, s23, 0
	s_mov_b32 s30, 1
	s_mov_b64 s[16:17], 0
	v_mov_b32_e32 v0, 0
	s_branch .LBB0_1295
